# strategy 4 variant: static s_setprio 1 for waves 0-3 (older half) instead of 4-7, flips deleted
# baseline (speedup 1.0000x reference)
.LBB0_120:
	s_mov_b32 s100, -1
	v_readlane_b32 s30, v254, 52
	v_readlane_b32 s40, v252, 4
	s_mul_i32 s25, s30, 0x8400
	v_readlane_b32 s44, v252, 8
	s_mul_hi_i32 s1, s30, 0x8400
	v_readlane_b32 s45, v252, 9
	s_add_u32 s68, s44, s25
	v_readlane_b32 s46, v252, 10
	s_addc_u32 s69, s45, s1
	s_mul_i32 s25, s30, 0x2c00
	v_readlane_b32 s47, v252, 11
	s_mul_hi_i32 s1, s30, 0x2c00
	s_add_u32 s70, s46, s25
	s_addc_u32 s71, s47, s1
	s_mul_i32 s25, s38, 0x1c00000
	v_readlane_b32 s20, v252, 32
	s_mul_hi_i32 s1, s38, 0x1c00000
	s_add_u32 s27, s20, s25
	v_readlane_b32 s20, v252, 33
	v_readlane_b32 s31, v254, 53
	s_addc_u32 s30, s20, s1
	s_mul_i32 s33, s38, 0xfea00000
	s_mul_hi_i32 s31, s38, 0xfea00000
	s_add_u32 s94, s27, s33
	s_addc_u32 s95, s30, s31
	s_add_u32 s25, s54, s25
	s_addc_u32 s1, s55, s1
	s_mul_i32 s30, s38, 0xffea0000
	s_mul_hi_i32 s27, s38, 0xffea0000
	s_add_u32 s25, s25, s30
	s_addc_u32 s1, s1, s27
	s_add_u32 s52, s25, 0x5600000
	s_addc_u32 s53, s1, 0
	s_add_u32 s50, s25, 0x5780000
	s_addc_u32 s51, s1, 0
	v_lshrrev_b32_e32 v15, 1, v14
	s_add_u32 s92, s25, 0x5900000
	v_and_b32_e32 v15, 24, v15
	s_addc_u32 s93, s1, 0
	v_and_b32_e32 v216, 15, v14
	s_lshl_b32 s1, s10, 6
	v_lshlrev_b32_e32 v16, 1, v15
	v_lshlrev_b32_e32 v14, 2, v14
	v_writelane_b32 v254, s1, 61
	v_lshl_or_b32 v16, v216, 6, v16
	s_lshl_b32 s1, s10, 13
	v_and_b32_e32 v14, 32, v14
	v_bitop3_b32 v17, v16, s1, v14 bitop3:0xde
	s_lshl_b32 s1, s11, 5
	s_and_b32 s1, s1, 0x60
	s_add_i32 m0, s75, 0x18000
	v_lshl_add_u64 v[6:7], v[6:7], 0, s[18:19]
	s_lshl_b32 s10, s1, 7
	s_waitcnt vmcnt(4)
	s_barrier
	global_load_lds_dwordx4 v[6:7], off
	v_lshl_add_u64 v[4:5], v[4:5], 0, s[18:19]
	s_add_i32 m0, s75, 0x1a000
	s_add_i32 s31, s75, 0x8000
	s_add_i32 s34, s75, 0xa000
	v_bitop3_b32 v217, v16, s10, v14 bitop3:0xde
	global_load_lds_dwordx4 v[4:5], off
	v_lshl_add_u64 v[2:3], v[2:3], 0, s[18:19]
	s_mov_b32 m0, s31
	s_add_u32 s10, s82, 0x40080
	global_load_lds_dwordx4 v[2:3], off
	v_lshl_add_u64 v[0:1], v[0:1], 0, s[18:19]
	s_mov_b32 m0, s34
	s_addc_u32 s11, s83, 0
	global_load_lds_dwordx4 v[0:1], off
	s_add_i32 m0, s75, 0x1c000
	v_lshl_add_u64 v[0:1], s[10:11], 0, v[144:145]
	global_load_lds_dwordx4 v[0:1], off
	v_lshl_add_u64 v[0:1], s[10:11], 0, v[162:163]
	s_add_i32 m0, s75, 0x1e000
	s_ashr_i32 s30, s8, 31
	global_load_lds_dwordx4 v[0:1], off
	v_lshlrev_b32_e32 v0, 14, v8
	v_and_b32_e32 v0, 0xffff8000, v0
	v_lshl_add_u32 v0, v9, 11, v0
	v_and_b32_e32 v1, 1, v8
	v_lshl_or_b32 v0, v1, 6, v0
	v_lshl_add_u32 v164, v10, 1, v0
	v_lshlrev_b32_e32 v0, 14, v11
	s_add_u32 s60, s68, 0x2c00
	v_and_b32_e32 v0, 0xffff8000, v0
	s_waitcnt vmcnt(6)
	s_addc_u32 s61, s69, 0
	v_lshl_add_u32 v0, v12, 11, v0
	v_and_b32_e32 v1, 1, v11
	v_readlane_b32 s41, v252, 5
	v_readlane_b32 s42, v252, 6
	v_readlane_b32 s43, v252, 7
	s_add_u32 s64, s68, 0x5800
	v_lshl_or_b32 v0, v1, 6, v0
	v_readlane_b32 s48, v252, 38
	s_mov_b32 s35, 0
	v_cmp_eq_u32_e64 s[38:39], 0, v216
	v_cmp_lt_u32_e64 s[40:41], 1, v216
	v_cmp_gt_u32_e64 s[42:43], 2, v216
	v_cmp_lt_u32_e64 s[44:45], 13, v216
	v_add_u32_e32 v218, -14, v216
	s_addc_u32 s65, s69, 0
	v_or_b32_e32 v219, s1, v15
	v_mov_b32_e32 v165, v145
	v_lshl_add_u32 v166, v13, 1, v0
	v_mov_b32_e32 v167, v145
	v_add_u32_e32 v220, 0, v17
	v_readlane_b32 s49, v252, 39
	s_barrier
	v_readfirstlane_b32 s101, v208
	s_nop 3
	s_lshr_b32 s101, s101, 8
	s_cmp_eq_u32 s101, 1
	s_cbranch_scc1 .Lprio_d_done
	s_setprio 1

.LBB0_181:
	v_readlane_b32 s20, v254, 47
	s_add_i32 s31, s20, 4
	s_cmp_lt_u32 s31, 11
	s_cselect_b64 s[34:35], -1, 0
	s_and_b64 s[34:35], s[34:35], s[0:1]
	v_readlane_b32 s56, v254, 23
	s_and_b64 s[34:35], s[34:35], exec
	v_readlane_b32 s57, v254, 24
	s_cselect_b32 s51, s57, 0
	s_cselect_b32 s50, s56, 0
	s_sub_i32 s31, s20, 25
	s_cmp_lt_u32 s31, -6
	s_cselect_b64 s[34:35], -1, 0
	s_or_b64 s[0:1], s[34:35], s[0:1]
	v_readlane_b32 s40, v252, 0
	s_and_b64 s[0:1], s[0:1], exec
	v_readlane_b32 s42, v252, 2
	v_readlane_b32 s43, v252, 3
	v_bfe_u32 v19, v18, 4, 2
	s_cselect_b32 s95, 0, s43
	s_cselect_b32 s94, 0, s42
	s_add_u32 s52, s54, s38
	v_and_b32_e32 v20, 15, v18
	v_lshlrev_b32_e32 v21, 4, v19
	v_lshlrev_b32_e32 v18, 2, v18
	s_addc_u32 s53, s55, s39
	v_lshl_or_b32 v206, s27, 6, v20
	v_lshl_or_b32 v20, v20, 6, v21
	s_lshl_b32 s0, s27, 13
	v_and_b32_e32 v18, 32, v18
	s_add_i32 m0, s85, 0x18000
	v_lshl_add_u64 v[0:1], v[0:1], 0, s[18:19]
	v_bitop3_b32 v21, v20, s0, v18 bitop3:0xde
	s_lshl_b32 s0, s30, 5
	s_waitcnt vmcnt(4)
	s_barrier
	global_load_lds_dwordx4 v[0:1], off
	v_lshl_add_u64 v[0:1], v[2:3], 0, s[18:19]
	s_add_i32 m0, s85, 0x1a000
	s_add_i32 s30, s85, 0x8000
	global_load_lds_dwordx4 v[0:1], off
	v_lshl_add_u64 v[0:1], v[4:5], 0, s[18:19]
	s_mov_b32 m0, s30
	s_add_i32 s31, s85, 0xa000
	global_load_lds_dwordx4 v[0:1], off
	v_lshl_add_u64 v[0:1], v[6:7], 0, s[18:19]
	s_mov_b32 m0, s31
	s_lshr_b32 s34, s25, 6
	global_load_lds_dwordx4 v[0:1], off
	s_add_i32 m0, s85, 0x1c000
	v_lshl_add_u64 v[0:1], v[8:9], 0, s[18:19]
	global_load_lds_dwordx4 v[0:1], off
	v_lshl_add_u64 v[0:1], v[10:11], 0, s[18:19]
	s_add_i32 m0, s85, 0x1e000
	s_and_b32 s0, s0, 0x60
	global_load_lds_dwordx4 v[0:1], off
	s_lshl_b32 s1, s0, 7
	s_add_i32 s82, s34, -2
	s_ashr_i32 s35, s29, 31
	v_add_u32_e32 v0, v14, v12
	s_cmp_lg_u64 s[50:51], 0
	v_add_lshl_u32 v0, v0, v13, 1
	v_mov_b32_e32 v1, v145
	s_waitcnt vmcnt(6)
	s_cselect_b64 s[92:93], -1, 0
	s_cmp_eq_u64 s[94:95], 0
	v_lshl_add_u64 v[190:191], s[98:99], 0, v[0:1]
	v_add_u32_e32 v0, v17, v15
	s_cselect_b64 s[72:73], -1, 0
	s_cmp_lg_u64 s[94:95], 0
	v_add_lshl_u32 v0, v0, v16, 1
	s_mov_b32 s81, 0
	v_bitop3_b32 v207, v20, s1, v18 bitop3:0xde
	v_cmp_eq_u32_e64 s[38:39], 0, v19
	s_cselect_b64 s[74:75], -1, 0
	v_lshl_or_b32 v216, v19, 3, s0
	v_lshl_add_u64 v[192:193], s[98:99], 0, v[0:1]
	v_add_u32_e32 v217, 0, v21
	v_readlane_b32 s58, v254, 25
	v_readlane_b32 s59, v254, 26
	v_readlane_b32 s60, v254, 27
	v_readlane_b32 s61, v254, 28
	v_readlane_b32 s62, v254, 29
	v_readlane_b32 s63, v254, 30
	v_readlane_b32 s64, v254, 31
	v_readlane_b32 s65, v254, 32
	v_readlane_b32 s66, v254, 33
	v_readlane_b32 s67, v254, 34
	v_readlane_b32 s68, v254, 35
	v_readlane_b32 s69, v254, 36
	v_readlane_b32 s70, v254, 37
	v_readlane_b32 s71, v254, 38
	v_readlane_b32 s41, v252, 1
	s_barrier
	v_readfirstlane_b32 s101, v208
	s_nop 3
	s_lshr_b32 s101, s101, 8
	s_cmp_eq_u32 s101, 1
	s_cbranch_scc1 .Lprio_ce_done
	s_setprio 1

.LBB0_321:
	v_readlane_b32 s1, v252, 32
	s_add_u32 s1, s1, s27
	v_readlane_b32 s8, v252, 33
	s_addc_u32 s10, s8, s10
	v_writelane_b32 v254, s36, 58
	s_lshl_b64 s[30:31], s[36:37], 22
	s_sub_u32 s27, 0, s30
	v_writelane_b32 v254, s37, 59
	s_subb_u32 s33, 0, s31
	s_add_u32 s96, s1, s27
	v_readlane_b32 s8, v254, 52
	s_addc_u32 s97, s10, s33
	s_lshl_b32 s30, s8, 6
	s_and_b32 s1, s25, 3
	s_add_i32 m0, s83, 0x18000
	v_lshl_add_u64 v[6:7], v[6:7], 0, s[18:19]
	s_ashr_i32 s31, s30, 31
	s_lshl_b32 s25, s11, 13
	s_lshl_b32 s36, s1, 12
	s_waitcnt vmcnt(4)
	s_barrier
	global_load_lds_dwordx4 v[6:7], off
	v_lshl_add_u64 v[4:5], v[4:5], 0, s[18:19]
	s_add_i32 m0, s83, 0x1a000
	s_add_i32 s87, s83, 0x8000
	s_add_i32 s79, s83, 0xa000
	global_load_lds_dwordx4 v[4:5], off
	v_lshl_add_u64 v[2:3], v[2:3], 0, s[18:19]
	s_mov_b32 m0, s87
	s_add_u32 s34, s72, 0x40080
	global_load_lds_dwordx4 v[2:3], off
	v_lshl_add_u64 v[0:1], v[0:1], 0, s[18:19]
	s_mov_b32 m0, s79
	s_addc_u32 s35, s73, 0
	global_load_lds_dwordx4 v[0:1], off
	s_add_i32 m0, s83, 0x1c000
	v_lshl_add_u64 v[0:1], s[34:35], 0, v[148:149]
	global_load_lds_dwordx4 v[0:1], off
	v_lshl_add_u64 v[0:1], s[34:35], 0, v[146:147]
	s_add_i32 m0, s83, 0x1e000
	v_readlane_b32 s9, v254, 53
	global_load_lds_dwordx4 v[0:1], off
	v_lshrrev_b32_e32 v0, 1, v9
	v_and_b32_e32 v0, 24, v0
	v_and_b32_e32 v1, 15, v9
	v_lshlrev_b32_e32 v2, 1, v0
	v_lshl_or_b32 v151, s11, 6, v1
	v_lshl_or_b32 v1, v1, 6, v2
	v_lshlrev_b32_e32 v2, 2, v9
	v_and_b32_e32 v2, 32, v2
	v_bitop3_b32 v3, v1, s25, v2 bitop3:0xde
	v_bitop3_b32 v216, v1, s36, v2 bitop3:0xde
	v_lshlrev_b32_e32 v1, 14, v12
	v_and_b32_e32 v1, 0xffff8000, v1
	v_lshl_or_b32 v150, s1, 6, v0
	v_writelane_b32 v254, s22, 60
	s_add_u32 s1, s22, s27
	v_lshl_add_u32 v1, v13, 11, v1
	v_and_b32_e32 v2, 1, v12
	v_writelane_b32 v254, s1, 52
	v_lshl_or_b32 v1, v2, 6, v1
	v_readlane_b32 s1, v254, 54
	v_lshl_add_u32 v152, v14, 1, v1
	v_lshlrev_b32_e32 v1, 14, v8
	s_addc_u32 s1, s1, s33
	v_and_b32_e32 v1, 0xffff8000, v1
	s_waitcnt vmcnt(6)
	v_writelane_b32 v254, s1, 61
	v_lshl_add_u32 v1, v10, 11, v1
	v_and_b32_e32 v2, 1, v8
	s_lshl_b64 s[8:9], s[30:31], 2
	v_lshl_or_b32 v1, v2, 6, v1
	v_writelane_b32 v254, s8, 62
	s_sext_i32_i8 s10, s38
	v_mov_b32_e32 v153, v145
	v_lshl_add_u32 v154, v11, 1, v1
	v_mov_b32_e32 v155, v145
	s_mov_b32 s22, 0
	v_add_u32_e32 v217, 0, v3
	v_writelane_b32 v254, s9, 63
	v_lshlrev_b32_e32 v218, 2, v0
	s_barrier
	v_readfirstlane_b32 s101, v208
	s_nop 3
	s_lshr_b32 s101, s101, 8
	s_cmp_eq_u32 s101, 1
	s_cbranch_scc1 .Lprio_a1_done
	s_setprio 1

.LBB0_341:
	s_lshl_b64 s[30:31], s[36:37], 13
	s_sub_u32 s30, 0, s30
	s_subb_u32 s31, 0, s31
	s_add_u32 s30, s22, s30
	v_readlane_b32 s22, v254, 54
	s_addc_u32 s31, s22, s31
	s_add_u32 s42, s30, 0x4c00000
	s_addc_u32 s43, s31, 0
	v_bfe_u32 v16, v8, 4, 2
	s_add_u32 s44, s30, 0x5000000
	v_and_b32_e32 v15, 15, v8
	v_lshlrev_b32_e32 v17, 4, v16
	v_lshlrev_b32_e32 v18, 2, v8
	s_addc_u32 s45, s31, 0
	v_lshl_or_b32 v190, s25, 6, v15
	v_lshl_or_b32 v17, v15, 6, v17
	s_lshl_b32 s25, s25, 13
	v_and_b32_e32 v18, 32, v18
	v_bitop3_b32 v19, v17, s25, v18 bitop3:0xde
	s_lshl_b32 s25, s27, 5
	s_and_b32 s79, s25, 0x60
	s_add_i32 m0, s77, 0x18000
	v_lshl_add_u64 v[6:7], v[6:7], 0, s[18:19]
	s_lshl_b32 s25, s79, 7
	s_waitcnt vmcnt(4)
	s_barrier
	global_load_lds_dwordx4 v[6:7], off
	v_lshl_add_u64 v[4:5], v[4:5], 0, s[18:19]
	s_add_i32 m0, s77, 0x1a000
	s_add_i32 s80, s77, 0x8000
	s_add_i32 s83, s77, 0xa000
	global_load_lds_dwordx4 v[4:5], off
	v_lshl_add_u64 v[2:3], v[2:3], 0, s[18:19]
	s_mov_b32 m0, s80
	s_add_u32 s30, s50, 0x40080
	global_load_lds_dwordx4 v[2:3], off
	v_lshl_add_u64 v[0:1], v[0:1], 0, s[18:19]
	s_mov_b32 m0, s83
	s_addc_u32 s31, s51, 0
	global_load_lds_dwordx4 v[0:1], off
	s_add_i32 m0, s77, 0x1c000
	v_lshl_add_u64 v[0:1], s[30:31], 0, v[148:149]
	global_load_lds_dwordx4 v[0:1], off
	v_lshl_add_u64 v[0:1], s[30:31], 0, v[152:153]
	s_add_i32 m0, s77, 0x1e000
	v_and_b32_e32 v3, 1, v9
	global_load_lds_dwordx4 v[0:1], off
	v_lshrrev_b32_e32 v1, 2, v8
	v_and_b32_e32 v2, 4, v1
	v_lshlrev_b32_e32 v1, 14, v9
	v_and_b32_e32 v1, 0xffff8000, v1
	v_lshl_add_u32 v1, v10, 11, v1
	v_lshl_or_b32 v1, v3, 6, v1
	v_lshl_add_u32 v156, v11, 1, v1
	v_lshlrev_b32_e32 v1, 14, v12
	v_and_b32_e32 v1, 0xffff8000, v1
	v_lshlrev_b32_e32 v191, 3, v16
	s_waitcnt vmcnt(6)
	v_readlane_b32 s30, v252, 36
	v_lshl_add_u32 v1, v13, 11, v1
	v_and_b32_e32 v3, 1, v12
	v_and_b32_e32 v0, 16, v191
	v_lshlrev_b32_e32 v144, 6, v16
	v_readlane_b32 s31, v252, 37
	v_lshl_or_b32 v1, v3, 6, v1
	s_sext_i32_i16 s11, s38
	v_bitop3_b32 v192, v17, s25, v18 bitop3:0xde
	v_add_u32_e32 v193, 0xfffffe00, v190
	s_mov_b32 s84, 0
	v_cmp_eq_u32_e64 s[38:39], 0, v15
	v_lshl_add_u64 v[154:155], s[30:31], 0, v[144:145]
	v_mov_b32_e32 v157, v145
	v_lshl_add_u32 v158, v14, 1, v1
	v_mov_b32_e32 v159, v145
	v_add_u32_e32 v194, 0, v19
	v_lshlrev_b32_e32 v144, 1, v0
	v_lshlrev_b32_e32 v160, 1, v2
	s_barrier
	v_readfirstlane_b32 s101, v208
	s_nop 3
	s_lshr_b32 s101, s101, 8
	s_cmp_eq_u32 s101, 1
	s_cbranch_scc1 .Lprio_a2_done
	s_setprio 1
